# attention: first V transpose-read group issued in the MFMA-to-VALU hazard slot (on top of HGRN wait fix and nt stores)
# baseline (speedup 1.0000x reference)
; __device__ __forceinline__ s16x4 tr_ld(ldsp p) { typedef short v4i16_t __attribute__((ext_vector_type(4))); return __builtin_bit_cast(s16x4, __builtin_amdgcn_ds_read_tr16_b64_v4i16((LAS v4i16_t*)p)); }
; __device__ __forceinline__ bf16x8 cat4(s16x4 a, s16x4 b) { return (bf16x8){a[0], a[1], a[2], a[3], b[0], b[1], b[2], b[3]}; }
; __device__ __forceinline__ bf16x8 pack8(const f32x16& x, int s) { u32x4 p; p[0] = cvtpk(x[8 * s], x[8 * s + 1]); p[1] = cvtpk(x[8 * s + 2], x[8 * s + 3]); p[2] = cvtpk(x[8 * s + 4], x[8 * s + 5]); p[3] = cvtpk(x[8 * s + 6], x[8 * s + 7]); return __builtin_bit_cast(bf16x8, p); }
; #define MFMA32(a, b, c) __builtin_amdgcn_mfma_f32_32x32x16_bf16((a), (b), (c), 0, 0, 0)
; __device__ __forceinline__ void attn_unit(ldsp L, int bh, int qb, const bf16* __restrict__ dq, const bf16* __restrict__ dk, const bf16* __restrict__ dv, bf16* __restrict__ ya, ...
;     ...
; #pragma unroll
;             for (int r = 0; r < 16; ++r) { p0[r] = __builtin_amdgcn_exp2f(p0[r]); p1[r] = __builtin_amdgcn_exp2f(p1[r]); }
;             bf16x8 pa[4]; pa[0] = pack8(p0, 0); pa[1] = pack8(p0, 1); pa[2] = pack8(p1, 0); pa[3] = pack8(p1, 1);
;             lacc = MFMA32(pa[0], ones, lacc); lacc = MFMA32(pa[1], ones, lacc); lacc = MFMA32(pa[2], ones, lacc); lacc = MFMA32(pa[3], ones, lacc);
;             const ldsp vbase = L + (t & 1) * A_STAGE + 2 * A_KT + (4 * hi + ((lane & 15) >> 2)) * A_VP + (16 * ((lane >> 4) & 1) + 4 * (lane & 3)) * 2;
; #pragma unroll
;             for (int s = 0; s < 4; ++s)
; #pragma unroll
;                 for (int vb = 0; vb < 4; ++vb) { const s16x4 lo = tr_ld(vbase + s * 16 * A_VP + vb * 64), hh = tr_ld(vbase + s * 16 * A_VP + 8 * A_VP + vb * 64);
;                     o[vb] = MFMA32(pa[s], cat4(lo, hh), o[vb]); }
.LBB0_800:
	v_add3_u32 v244, s13, v207, v219
	ds_read_b64_tr_b16 v[230:231], v244 offset:20992
	ds_read_b64_tr_b16 v[228:229], v244 offset:18432
	ds_read_b64_tr_b16 v[232:233], v244 offset:18496
	ds_read_b64_tr_b16 v[236:237], v244 offset:18560
	ds_read_b64_tr_b16 v[240:241], v244 offset:18624
	ds_read_b64_tr_b16 v[234:235], v244 offset:21056
	ds_read_b64_tr_b16 v[238:239], v244 offset:21120
	ds_read_b64_tr_b16 v[242:243], v244 offset:21184
	s_nop 0
	v_exp_f32_e32 v0, v112
	v_exp_f32_e32 v2, v113
	v_exp_f32_e32 v3, v114
	v_exp_f32_e32 v4, v115
	v_exp_f32_e32 v5, v116
	v_exp_f32_e32 v6, v117
	v_exp_f32_e32 v7, v118
	v_exp_f32_e32 v8, v119
	v_cvt_pk_bf16_f32 v2, v0, v2
	v_cvt_pk_bf16_f32 v3, v3, v4
	v_cvt_pk_bf16_f32 v4, v5, v6
	v_cvt_pk_bf16_f32 v5, v7, v8
	v_add3_u32 v0, s13, v207, v219
	s_waitcnt lgkmcnt(6)
	v_mfma_f32_32x32x16_bf16 v[64:79], v[2:5], v[228:231], v[64:79]
	v_exp_f32_e32 v6, v120
	v_exp_f32_e32 v7, v121
	v_exp_f32_e32 v8, v122
	v_exp_f32_e32 v9, v123
	v_exp_f32_e32 v14, v100
	v_cvt_pk_bf16_f32 v6, v6, v7
	v_exp_f32_e32 v15, v101
	s_waitcnt lgkmcnt(2)
	v_mfma_f32_32x32x16_bf16 v[48:63], v[2:5], v[232:235], v[48:63]
	v_exp_f32_e32 v10, v124
	v_exp_f32_e32 v11, v125
	v_exp_f32_e32 v12, v126
	v_exp_f32_e32 v13, v127
	v_cvt_pk_bf16_f32 v7, v8, v9
	v_cvt_pk_bf16_f32 v8, v10, v11
	s_mov_b32 s14, s12
	v_cvt_pk_bf16_f32 v9, v12, v13
	s_waitcnt lgkmcnt(1)
	v_mfma_f32_32x32x16_bf16 v[32:47], v[2:5], v[236:239], v[32:47]
	s_mov_b32 s15, s12
	s_mov_b32 s13, s12
	s_waitcnt lgkmcnt(0)
	v_mfma_f32_32x32x16_bf16 v[16:31], v[2:5], v[240:243], v[16:31]
	ds_read_b64_tr_b16 v[12:13], v0 offset:26112
	ds_read_b64_tr_b16 v[10:11], v0 offset:23552
	ds_read_b64_tr_b16 v[112:113], v0 offset:23616
	ds_read_b64_tr_b16 v[116:117], v0 offset:23680
	ds_read_b64_tr_b16 v[120:121], v0 offset:23744
	ds_read_b64_tr_b16 v[114:115], v0 offset:26176
	ds_read_b64_tr_b16 v[118:119], v0 offset:26240
	ds_read_b64_tr_b16 v[122:123], v0 offset:26304
	s_waitcnt lgkmcnt(6)
	v_mfma_f32_32x32x16_bf16 v[64:79], v[6:9], v[10:13], v[64:79]
	v_exp_f32_e32 v10, v96
	v_exp_f32_e32 v11, v97
	v_exp_f32_e32 v12, v98
	v_exp_f32_e32 v13, v99
	v_exp_f32_e32 v96, v102
	v_exp_f32_e32 v97, v103
	v_cvt_pk_bf16_f32 v10, v10, v11
	s_waitcnt lgkmcnt(2)
	v_mfma_f32_32x32x16_bf16 v[48:63], v[6:9], v[112:115], v[48:63]
	v_cvt_pk_bf16_f32 v11, v12, v13
	v_cvt_pk_bf16_f32 v12, v14, v15
	v_cvt_pk_bf16_f32 v13, v96, v97
	v_exp_f32_e32 v14, v104
	v_exp_f32_e32 v15, v105
	s_waitcnt lgkmcnt(1)
	v_mfma_f32_32x32x16_bf16 v[32:47], v[6:9], v[116:119], v[32:47]
	ds_read_b64_tr_b16 v[98:99], v0 offset:31232
	ds_read_b64_tr_b16 v[96:97], v0 offset:28672
	ds_read_b64_tr_b16 v[100:101], v0 offset:28736
	ds_read_b64_tr_b16 v[112:113], v0 offset:28800
	ds_read_b64_tr_b16 v[116:117], v0 offset:28864
	ds_read_b64_tr_b16 v[102:103], v0 offset:31296
	ds_read_b64_tr_b16 v[114:115], v0 offset:31360
	ds_read_b64_tr_b16 v[118:119], v0 offset:31424
	s_waitcnt lgkmcnt(6)
	v_mfma_f32_32x32x16_bf16 v[64:79], v[10:13], v[96:99], v[64:79]
	v_exp_f32_e32 v97, v106
	v_exp_f32_e32 v98, v107
	v_exp_f32_e32 v99, v108
	v_cvt_pk_bf16_f32 v96, v14, v15
	v_cvt_pk_bf16_f32 v97, v97, v98
	s_waitcnt lgkmcnt(2)
	v_mfma_f32_32x32x16_bf16 v[48:63], v[10:13], v[100:103], v[48:63]
	v_exp_f32_e32 v100, v109
	v_exp_f32_e32 v101, v110
	v_exp_f32_e32 v102, v111
	v_cvt_pk_bf16_f32 v98, v99, v100
	v_cvt_pk_bf16_f32 v99, v101, v102
	s_waitcnt lgkmcnt(1)
	v_mfma_f32_32x32x16_bf16 v[32:47], v[10:13], v[112:115], v[32:47]
	ds_read_b64_tr_b16 v[102:103], v0 offset:36352
	ds_read_b64_tr_b16 v[100:101], v0 offset:33792
	ds_read_b64_tr_b16 v[104:105], v0 offset:33856
	ds_read_b64_tr_b16 v[108:109], v0 offset:33920
	ds_read_b64_tr_b16 v[112:113], v0 offset:33984
	ds_read_b64_tr_b16 v[106:107], v0 offset:36416
	ds_read_b64_tr_b16 v[110:111], v0 offset:36480
	ds_read_b64_tr_b16 v[114:115], v0 offset:36544
	s_waitcnt lgkmcnt(6)
	v_mfma_f32_32x32x16_bf16 v[64:79], v[96:99], v[100:103], v[64:79]
	v_mov_b64_e32 v[102:103], s[14:15]
	v_mov_b64_e32 v[100:101], s[12:13]
	s_nop 1
	v_mfma_f32_32x32x16_bf16 v[80:95], v[2:5], v[100:103], v[80:95]
	v_mfma_f32_32x32x16_bf16 v[16:31], v[6:9], v[120:123], v[16:31]
	v_mfma_f32_32x32x16_bf16 v[80:95], v[6:9], v[100:103], v[80:95]
	v_mfma_f32_32x32x16_bf16 v[16:31], v[10:13], v[116:119], v[16:31]
	v_mfma_f32_32x32x16_bf16 v[80:95], v[10:13], v[100:103], v[80:95]
	s_waitcnt lgkmcnt(2)
	v_mfma_f32_32x32x16_bf16 v[48:63], v[96:99], v[104:107], v[48:63]
	s_waitcnt lgkmcnt(1)
	v_mfma_f32_32x32x16_bf16 v[32:47], v[96:99], v[108:111], v[32:47]
	s_waitcnt lgkmcnt(0)
	v_mfma_f32_32x32x16_bf16 v[16:31], v[96:99], v[112:115], v[16:31]
	v_mfma_f32_32x32x16_bf16 v[80:95], v[96:99], v[100:103], v[80:95]
